# skip the final grid barrier after the last layer (kernel end provides completion)
# speedup vs baseline: 1.0059x; 1.0059x over previous
.LBB0_916:
	s_or_b64 exec, exec, s[10:11]
	s_cmp_eq_u32 s27, 3
	s_cbranch_scc1 .LBB0_963
	s_waitcnt vmcnt(0)
	s_barrier
	s_mov_b64 s[10:11], exec
	v_readlane_b32 s0, v254, 3
	v_readlane_b32 s1, v254, 4
	s_and_b64 s[0:1], s[10:11], s[0:1]
	s_mov_b64 exec, s[0:1]
	s_cbranch_execz .LBB0_301
	v_readlane_b32 s0, v255, 32
	s_waitcnt vmcnt(0) expcnt(0) lgkmcnt(0)
	s_nop 0
	v_mov_b32_e32 v0, s0
	ds_read_b32 v2, v0
	v_readlane_b32 s0, v255, 33
	s_waitcnt lgkmcnt(0)
	v_cmp_ne_u32_e32 vcc, 0, v2
	v_mov_b32_e32 v0, s0
	ds_read_b32 v0, v0
	s_cbranch_vccnz .LBB0_932
	s_mov_b32 s2, 1
	s_branch .LBB0_920
